# diff-attention finalize: preload o_subln_g once, no per-store reload/wait
# baseline (speedup 1.0000x reference)
.LBB0_1698:
	s_or_b64 exec, exec, s[2:3]
	s_waitcnt lgkmcnt(0)
	s_barrier
	s_and_saveexec_b64 s[0:1], vcc
	s_cbranch_execz .LBB0_1700
	v_readlane_b32 s76, v254, 50
	ds_read2st64_b32 v[72:73], v65 offset1:2
	ds_read2st64_b32 v[68:69], v65 offset0:4 offset1:6
	ds_read2st64_b32 v[74:75], v65 offset0:16 offset1:18
	ds_read2st64_b32 v[76:77], v65 offset0:20 offset1:22
	ds_read2st64_b32 v[78:79], v65 offset0:32 offset1:34
	ds_read2st64_b32 v[80:81], v65 offset0:36 offset1:38
	ds_read2st64_b32 v[82:83], v65 offset0:48 offset1:50
	ds_read2st64_b32 v[84:85], v65 offset0:52 offset1:54
	ds_read2st64_b32 v[86:87], v65 offset0:64 offset1:66
	ds_read2st64_b32 v[88:89], v65 offset0:68 offset1:70
	ds_read2st64_b32 v[90:91], v65 offset0:80 offset1:82
	ds_read2st64_b32 v[92:93], v65 offset0:84 offset1:86
	ds_read2st64_b32 v[94:95], v65 offset0:96 offset1:98
	ds_read2st64_b32 v[96:97], v65 offset0:100 offset1:102
	ds_read2st64_b32 v[98:99], v65 offset0:112 offset1:114
	ds_read2st64_b32 v[100:101], v65 offset0:116 offset1:118
	v_lshlrev_b32_e32 v67, 4, v125
	v_readlane_b32 s80, v254, 54
	v_readlane_b32 s81, v254, 55
	s_waitcnt lgkmcnt(14)
	v_pk_fma_f32 v[62:63], v[62:63], v[66:67], v[68:69] op_sel_hi:[1,0,1] neg_lo:[0,0,1] neg_hi:[0,0,1]
	v_pk_fma_f32 v[60:61], v[60:61], v[66:67], v[72:73] op_sel_hi:[1,0,1] neg_lo:[0,0,1] neg_hi:[0,0,1]
	v_mul_f32_e32 v104, v63, v63
	v_mul_f32_e32 v72, v61, v61
	v_pk_fma_f32 v[72:73], v[60:61], v[60:61], v[72:73] op_sel_hi:[1,1,0]
	global_load_dwordx4 v[68:71], v67, s[80:81]
	global_load_dwordx4 v[218:221], v67, s[80:81] offset:64
	global_load_dwordx4 v[222:225], v67, s[80:81] offset:128
	global_load_dwordx4 v[226:229], v67, s[80:81] offset:192
	global_load_dwordx4 v[230:233], v67, s[80:81] offset:256
	global_load_dwordx4 v[234:237], v67, s[80:81] offset:320
	global_load_dwordx4 v[238:241], v67, s[80:81] offset:384
	global_load_dwordx4 v[242:245], v67, s[80:81] offset:448
	global_load_dwordx4 v[246:249], v67, s[80:81]
	v_pk_fma_f32 v[72:73], v[62:63], v[62:63], v[72:73]
	s_waitcnt lgkmcnt(13)
	v_pk_fma_f32 v[48:49], v[48:49], v[66:67], v[74:75] op_sel_hi:[1,0,1] neg_lo:[0,0,1] neg_hi:[0,0,1]
	v_pk_add_f32 v[72:73], v[72:73], v[104:105] op_sel_hi:[1,0]
	v_mul_f32_e32 v74, v49, v49
	v_pk_fma_f32 v[72:73], v[48:49], v[48:49], v[72:73]
	s_waitcnt lgkmcnt(12)
	v_pk_fma_f32 v[50:51], v[50:51], v[66:67], v[76:77] op_sel_hi:[1,0,1] neg_lo:[0,0,1] neg_hi:[0,0,1]
	v_pk_add_f32 v[72:73], v[72:73], v[74:75] op_sel_hi:[1,0]
	v_mul_f32_e32 v74, v51, v51
	v_pk_fma_f32 v[72:73], v[50:51], v[50:51], v[72:73]
	s_waitcnt lgkmcnt(11)
	v_pk_fma_f32 v[40:41], v[40:41], v[66:67], v[78:79] op_sel_hi:[1,0,1] neg_lo:[0,0,1] neg_hi:[0,0,1]
	v_pk_add_f32 v[72:73], v[72:73], v[74:75] op_sel_hi:[1,0]
	v_mul_f32_e32 v74, v41, v41
	v_pk_fma_f32 v[72:73], v[40:41], v[40:41], v[72:73]
	s_waitcnt lgkmcnt(10)
	v_pk_fma_f32 v[42:43], v[42:43], v[66:67], v[80:81] op_sel_hi:[1,0,1] neg_lo:[0,0,1] neg_hi:[0,0,1]
	v_pk_add_f32 v[72:73], v[72:73], v[74:75] op_sel_hi:[1,0]
	v_mul_f32_e32 v74, v43, v43
	v_pk_fma_f32 v[72:73], v[42:43], v[42:43], v[72:73]
	s_waitcnt lgkmcnt(9)
	v_pk_fma_f32 v[76:77], v[32:33], v[66:67], v[82:83] op_sel_hi:[1,0,1] neg_lo:[0,0,1] neg_hi:[0,0,1]
	v_pk_add_f32 v[72:73], v[72:73], v[74:75] op_sel_hi:[1,0]
	s_waitcnt lgkmcnt(8)
	v_pk_fma_f32 v[74:75], v[34:35], v[66:67], v[84:85] op_sel_hi:[1,0,1] neg_lo:[0,0,1] neg_hi:[0,0,1]
	v_pk_fma_f32 v[32:33], v[76:77], v[76:77], v[72:73]
	v_mul_f32_e32 v34, v77, v77
	v_pk_add_f32 v[32:33], v[32:33], v[34:35] op_sel_hi:[1,0]
	v_mul_f32_e32 v34, v75, v75
	v_pk_fma_f32 v[32:33], v[74:75], v[74:75], v[32:33]
	s_waitcnt lgkmcnt(7)
	v_pk_fma_f32 v[52:53], v[52:53], v[66:67], v[86:87] op_sel_hi:[1,0,1] neg_lo:[0,0,1] neg_hi:[0,0,1]
	v_pk_add_f32 v[32:33], v[32:33], v[34:35] op_sel_hi:[1,0]
	v_mul_f32_e32 v34, v53, v53
	v_pk_fma_f32 v[32:33], v[52:53], v[52:53], v[32:33]
	s_waitcnt lgkmcnt(6)
	v_pk_fma_f32 v[54:55], v[54:55], v[66:67], v[88:89] op_sel_hi:[1,0,1] neg_lo:[0,0,1] neg_hi:[0,0,1]
	v_pk_add_f32 v[32:33], v[32:33], v[34:35] op_sel_hi:[1,0]
	v_mul_f32_e32 v34, v55, v55
	v_pk_fma_f32 v[32:33], v[54:55], v[54:55], v[32:33]
	s_waitcnt lgkmcnt(5)
	v_pk_fma_f32 v[44:45], v[44:45], v[66:67], v[90:91] op_sel_hi:[1,0,1] neg_lo:[0,0,1] neg_hi:[0,0,1]
	v_pk_add_f32 v[32:33], v[32:33], v[34:35] op_sel_hi:[1,0]
	v_mul_f32_e32 v34, v45, v45
	v_pk_fma_f32 v[32:33], v[44:45], v[44:45], v[32:33]
	s_waitcnt lgkmcnt(4)
	v_pk_fma_f32 v[46:47], v[46:47], v[66:67], v[92:93] op_sel_hi:[1,0,1] neg_lo:[0,0,1] neg_hi:[0,0,1]
	v_pk_add_f32 v[32:33], v[32:33], v[34:35] op_sel_hi:[1,0]
	v_mul_f32_e32 v34, v47, v47
	v_pk_fma_f32 v[32:33], v[46:47], v[46:47], v[32:33]
	s_waitcnt lgkmcnt(3)
	v_pk_fma_f32 v[36:37], v[36:37], v[66:67], v[94:95] op_sel_hi:[1,0,1] neg_lo:[0,0,1] neg_hi:[0,0,1]
	v_pk_add_f32 v[32:33], v[32:33], v[34:35] op_sel_hi:[1,0]
	v_mul_f32_e32 v34, v37, v37
	v_pk_fma_f32 v[32:33], v[36:37], v[36:37], v[32:33]
	s_waitcnt lgkmcnt(2)
	v_pk_fma_f32 v[38:39], v[38:39], v[66:67], v[96:97] op_sel_hi:[1,0,1] neg_lo:[0,0,1] neg_hi:[0,0,1]
	v_pk_add_f32 v[32:33], v[32:33], v[34:35] op_sel_hi:[1,0]
	v_mul_f32_e32 v34, v39, v39
	v_pk_fma_f32 v[32:33], v[38:39], v[38:39], v[32:33]
	s_waitcnt lgkmcnt(1)
	v_pk_fma_f32 v[56:57], v[56:57], v[66:67], v[98:99] op_sel_hi:[1,0,1] neg_lo:[0,0,1] neg_hi:[0,0,1]
	v_pk_add_f32 v[32:33], v[32:33], v[34:35] op_sel_hi:[1,0]
	v_mul_f32_e32 v34, v57, v57
	v_pk_fma_f32 v[32:33], v[56:57], v[56:57], v[32:33]
	s_waitcnt lgkmcnt(0)
	v_pk_fma_f32 v[58:59], v[58:59], v[66:67], v[100:101] op_sel_hi:[1,0,1] neg_lo:[0,0,1] neg_hi:[0,0,1]
	v_pk_add_f32 v[32:33], v[32:33], v[34:35] op_sel_hi:[1,0]
	v_mul_f32_e32 v34, v59, v59
	v_pk_fma_f32 v[32:33], v[58:59], v[58:59], v[32:33]
	v_readlane_b32 s4, v253, 50
	v_pk_add_f32 v[32:33], v[32:33], v[34:35] op_sel_hi:[1,0]
	v_lshlrev_b64 v[102:103], 11, v[130:131]
	v_mov_b32_e32 v33, v32
	s_nop 1
	v_permlane16_swap_b32_e32 v32, v33
	v_add_f32_e32 v32, v32, v33
	v_mov_b32_e32 v33, v32
	s_nop 1
	v_permlane32_swap_b32_e32 v32, v33
	v_add_f32_e32 v32, v32, v33
	v_fmamk_f32 v32, v32, 0x3c000000, v182
	v_mul_f32_e32 v33, 0x4b800000, v32
	v_cmp_gt_f32_e32 vcc, s40, v32
	v_readlane_b32 s16, v253, 62
	v_readlane_b32 s17, v253, 63
	v_cndmask_b32_e32 v32, v32, v33, vcc
	v_rsq_f32_e32 v34, v32
	v_lshl_add_u64 v[102:103], s[16:17], 0, v[102:103]
	s_lshl_b32 s46, s21, 1
	v_lshl_add_u64 v[32:33], v[102:103], 0, s[46:47]
	v_mov_b32_e32 v125, v129
	v_lshl_add_u64 v[72:73], v[32:33], 0, v[124:125]
	v_mul_f32_e32 v32, 0x45800000, v34
	v_cndmask_b32_e32 v32, v34, v32, vcc
	v_mul_f32_e32 v66, 0x3f24fd5c, v32
	v_pk_mul_f32 v[32:33], v[60:61], v[66:67] op_sel_hi:[1,0]
	v_pk_mul_f32 v[34:35], v[62:63], v[66:67] op_sel_hi:[1,0]
	s_waitcnt vmcnt(0)
	v_pk_mul_f32 v[32:33], v[68:69], v[32:33]
	v_pk_mul_f32 v[34:35], v[70:71], v[34:35]
	v_cvt_pk_bf16_f32 v32, v32, v33
	v_cvt_pk_bf16_f32 v33, v34, v35
	global_store_dwordx2 v[72:73], v[32:33], off offset:1024
	v_mov_b64_e32 v[32:33], v[218:219]
	v_mov_b64_e32 v[34:35], v[220:221]
	v_pk_mul_f32 v[48:49], v[48:49], v[66:67] op_sel_hi:[1,0]
	v_pk_mul_f32 v[50:51], v[50:51], v[66:67] op_sel_hi:[1,0]
	v_pk_mul_f32 v[40:41], v[40:41], v[66:67] op_sel_hi:[1,0]
	v_pk_mul_f32 v[42:43], v[42:43], v[66:67] op_sel_hi:[1,0]
	v_pk_mul_f32 v[36:37], v[36:37], v[66:67] op_sel_hi:[1,0]
	v_pk_mul_f32 v[38:39], v[38:39], v[66:67] op_sel_hi:[1,0]
	v_lshlrev_b64 v[78:79], 11, v[126:127]
	v_readlane_b32 s77, v254, 51
	v_readlane_b32 s78, v254, 52
	v_readlane_b32 s79, v254, 53
	v_readlane_b32 s82, v254, 56
	v_readlane_b32 s83, v254, 57
	v_readlane_b32 s84, v254, 58
	v_readlane_b32 s85, v254, 59
	v_readlane_b32 s86, v254, 60
	v_readlane_b32 s87, v254, 61
	v_readlane_b32 s88, v254, 62
	v_readlane_b32 s89, v254, 63
	v_readlane_b32 s90, v253, 0
	v_readlane_b32 s91, v253, 1
	v_readlane_b32 s5, v253, 51
	v_readlane_b32 s6, v253, 52
	v_readlane_b32 s7, v253, 53
	v_readlane_b32 s8, v253, 54
	v_readlane_b32 s9, v253, 55
	v_readlane_b32 s10, v253, 56
	v_readlane_b32 s11, v253, 57
	v_readlane_b32 s12, v253, 58
	v_readlane_b32 s13, v253, 59
	v_readlane_b32 s14, v253, 60
	v_readlane_b32 s15, v253, 61
	v_readlane_b32 s18, v255, 0
	v_readlane_b32 s19, v255, 1
	v_pk_mul_f32 v[32:33], v[32:33], v[48:49]
	v_pk_mul_f32 v[34:35], v[34:35], v[50:51]
	v_cvt_pk_bf16_f32 v32, v32, v33
	v_cvt_pk_bf16_f32 v33, v34, v35
	global_store_dwordx2 v[72:73], v[32:33], off offset:1056
	v_mov_b64_e32 v[32:33], v[222:223]
	v_mov_b64_e32 v[34:35], v[224:225]
	v_pk_mul_f32 v[32:33], v[40:41], v[32:33]
	v_pk_mul_f32 v[34:35], v[42:43], v[34:35]
	v_cvt_pk_bf16_f32 v32, v32, v33
	v_cvt_pk_bf16_f32 v33, v34, v35
	global_store_dwordx2 v[72:73], v[32:33], off offset:1088
	v_mov_b64_e32 v[32:33], v[226:227]
	v_mov_b64_e32 v[34:35], v[228:229]
	v_pk_mul_f32 v[40:41], v[76:77], v[66:67] op_sel_hi:[1,0]
	v_pk_mul_f32 v[42:43], v[74:75], v[66:67] op_sel_hi:[1,0]
	v_pk_mul_f32 v[32:33], v[40:41], v[32:33]
	v_pk_mul_f32 v[34:35], v[42:43], v[34:35]
	v_cvt_pk_bf16_f32 v32, v32, v33
	v_cvt_pk_bf16_f32 v33, v34, v35
	global_store_dwordx2 v[72:73], v[32:33], off offset:1120
	v_mov_b64_e32 v[32:33], v[230:231]
	v_mov_b64_e32 v[34:35], v[232:233]
	v_pk_mul_f32 v[40:41], v[52:53], v[66:67] op_sel_hi:[1,0]
	v_pk_mul_f32 v[42:43], v[54:55], v[66:67] op_sel_hi:[1,0]
	v_pk_mul_f32 v[32:33], v[40:41], v[32:33]
	v_pk_mul_f32 v[34:35], v[42:43], v[34:35]
	v_cvt_pk_bf16_f32 v32, v32, v33
	v_cvt_pk_bf16_f32 v33, v34, v35
	global_store_dwordx2 v[72:73], v[32:33], off offset:1152
	v_mov_b64_e32 v[32:33], v[234:235]
	v_mov_b64_e32 v[34:35], v[236:237]
	v_pk_mul_f32 v[40:41], v[44:45], v[66:67] op_sel_hi:[1,0]
	v_pk_mul_f32 v[42:43], v[46:47], v[66:67] op_sel_hi:[1,0]
	v_pk_mul_f32 v[32:33], v[40:41], v[32:33]
	v_pk_mul_f32 v[34:35], v[42:43], v[34:35]
	v_cvt_pk_bf16_f32 v32, v32, v33
	v_cvt_pk_bf16_f32 v33, v34, v35
	global_store_dwordx2 v[72:73], v[32:33], off offset:1184
	v_mov_b64_e32 v[32:33], v[238:239]
	v_mov_b64_e32 v[34:35], v[240:241]
	v_pk_mul_f32 v[32:33], v[36:37], v[32:33]
	v_pk_mul_f32 v[34:35], v[38:39], v[34:35]
	v_cvt_pk_bf16_f32 v32, v32, v33
	v_cvt_pk_bf16_f32 v33, v34, v35
	global_store_dwordx2 v[72:73], v[32:33], off offset:1216
	v_mov_b64_e32 v[32:33], v[242:243]
	v_mov_b64_e32 v[34:35], v[244:245]
	ds_read2st64_b32 v[36:37], v65 offset0:8 offset1:10
	ds_read2st64_b32 v[38:39], v65 offset0:12 offset1:14
	ds_read2st64_b32 v[40:41], v65 offset0:24 offset1:26
	ds_read2st64_b32 v[42:43], v65 offset0:28 offset1:30
	ds_read2st64_b32 v[44:45], v65 offset0:40 offset1:42
	ds_read2st64_b32 v[46:47], v65 offset0:44 offset1:46
	ds_read2st64_b32 v[48:49], v65 offset0:56 offset1:58
	ds_read2st64_b32 v[50:51], v65 offset0:60 offset1:62
	ds_read2st64_b32 v[52:53], v65 offset0:72 offset1:74
	ds_read2st64_b32 v[54:55], v65 offset0:76 offset1:78
	ds_read2st64_b32 v[60:61], v65 offset0:88 offset1:90
	ds_read2st64_b32 v[62:63], v65 offset0:92 offset1:94
	ds_read2st64_b32 v[68:69], v65 offset0:104 offset1:106
	ds_read2st64_b32 v[70:71], v65 offset0:108 offset1:110
	ds_read2st64_b32 v[74:75], v65 offset0:120 offset1:122
	ds_read2st64_b32 v[76:77], v65 offset0:124 offset1:126
	s_waitcnt lgkmcnt(14)
	v_pk_fma_f32 v[38:39], v[26:27], v[64:65], v[38:39] op_sel_hi:[1,0,1] neg_lo:[0,0,1] neg_hi:[0,0,1]
	v_pk_fma_f32 v[36:37], v[24:25], v[64:65], v[36:37] op_sel_hi:[1,0,1] neg_lo:[0,0,1] neg_hi:[0,0,1]
	v_pk_mul_f32 v[24:25], v[56:57], v[66:67] op_sel_hi:[1,0]
	v_pk_mul_f32 v[26:27], v[58:59], v[66:67] op_sel_hi:[1,0]
	s_waitcnt lgkmcnt(13)
	v_pk_fma_f32 v[28:29], v[28:29], v[64:65], v[40:41] op_sel_hi:[1,0,1] neg_lo:[0,0,1] neg_hi:[0,0,1]
	s_waitcnt lgkmcnt(12)
	v_pk_fma_f32 v[30:31], v[30:31], v[64:65], v[42:43] op_sel_hi:[1,0,1] neg_lo:[0,0,1] neg_hi:[0,0,1]
	v_mul_f32_e32 v40, v29, v29
	v_mul_f32_e32 v42, v31, v31
	s_waitcnt lgkmcnt(11)
	v_pk_fma_f32 v[8:9], v[8:9], v[64:65], v[44:45] op_sel_hi:[1,0,1] neg_lo:[0,0,1] neg_hi:[0,0,1]
	s_waitcnt lgkmcnt(10)
	v_pk_fma_f32 v[10:11], v[10:11], v[64:65], v[46:47] op_sel_hi:[1,0,1] neg_lo:[0,0,1] neg_hi:[0,0,1]
	v_mul_f32_e32 v44, v9, v9
	v_mul_f32_e32 v46, v11, v11
	s_waitcnt lgkmcnt(7)
	v_pk_fma_f32 v[16:17], v[16:17], v[64:65], v[52:53] op_sel_hi:[1,0,1] neg_lo:[0,0,1] neg_hi:[0,0,1]
	s_waitcnt lgkmcnt(6)
	v_pk_fma_f32 v[18:19], v[18:19], v[64:65], v[54:55] op_sel_hi:[1,0,1] neg_lo:[0,0,1] neg_hi:[0,0,1]
	v_mul_f32_e32 v52, v17, v17
	v_mul_f32_e32 v54, v19, v19
	s_waitcnt lgkmcnt(5)
	v_pk_fma_f32 v[12:13], v[12:13], v[64:65], v[60:61] op_sel_hi:[1,0,1] neg_lo:[0,0,1] neg_hi:[0,0,1]
	s_waitcnt lgkmcnt(4)
	v_pk_fma_f32 v[14:15], v[14:15], v[64:65], v[62:63] op_sel_hi:[1,0,1] neg_lo:[0,0,1] neg_hi:[0,0,1]
	v_mul_f32_e32 v56, v13, v13
	v_mul_f32_e32 v58, v15, v15
	s_waitcnt lgkmcnt(3)
	v_pk_fma_f32 v[4:5], v[4:5], v[64:65], v[68:69] op_sel_hi:[1,0,1] neg_lo:[0,0,1] neg_hi:[0,0,1]
	s_waitcnt lgkmcnt(2)
	v_pk_fma_f32 v[6:7], v[6:7], v[64:65], v[70:71] op_sel_hi:[1,0,1] neg_lo:[0,0,1] neg_hi:[0,0,1]
	v_mul_f32_e32 v60, v5, v5
	v_mul_f32_e32 v62, v7, v7
	s_waitcnt lgkmcnt(1)
	v_pk_fma_f32 v[20:21], v[20:21], v[64:65], v[74:75] op_sel_hi:[1,0,1] neg_lo:[0,0,1] neg_hi:[0,0,1]
	s_waitcnt lgkmcnt(0)
	v_pk_fma_f32 v[22:23], v[22:23], v[64:65], v[76:77] op_sel_hi:[1,0,1] neg_lo:[0,0,1] neg_hi:[0,0,1]
	v_pk_mul_f32 v[24:25], v[24:25], v[32:33]
	v_pk_mul_f32 v[26:27], v[26:27], v[34:35]
	v_cvt_pk_bf16_f32 v24, v24, v25
	v_cvt_pk_bf16_f32 v25, v26, v27
	global_store_dwordx2 v[72:73], v[24:25], off offset:1248
	v_mov_b64_e32 v[24:25], v[246:247]
	v_mov_b64_e32 v[26:27], v[248:249]
	v_pk_fma_f32 v[34:35], v[0:1], v[64:65], v[48:49] op_sel_hi:[1,0,1] neg_lo:[0,0,1] neg_hi:[0,0,1]
	v_mul_f32_e32 v0, v37, v37
	v_pk_fma_f32 v[0:1], v[36:37], v[36:37], v[0:1] op_sel_hi:[1,1,0]
	v_pk_fma_f32 v[32:33], v[2:3], v[64:65], v[50:51] op_sel_hi:[1,0,1] neg_lo:[0,0,1] neg_hi:[0,0,1]
	v_mul_f32_e32 v2, v39, v39
	v_pk_fma_f32 v[0:1], v[38:39], v[38:39], v[0:1]
	v_mul_f32_e32 v48, v35, v35
	v_pk_add_f32 v[0:1], v[0:1], v[2:3] op_sel_hi:[1,0]
	v_mul_f32_e32 v50, v33, v33
	v_pk_fma_f32 v[0:1], v[28:29], v[28:29], v[0:1]
	v_mul_f32_e32 v64, v21, v21
	v_pk_add_f32 v[0:1], v[0:1], v[40:41] op_sel_hi:[1,0]
	v_mul_f32_e32 v66, v23, v23
	v_pk_fma_f32 v[0:1], v[30:31], v[30:31], v[0:1]
	s_nop 0
	v_pk_add_f32 v[0:1], v[0:1], v[42:43] op_sel_hi:[1,0]
	s_nop 0
	v_pk_fma_f32 v[0:1], v[8:9], v[8:9], v[0:1]
	s_nop 0
	v_pk_add_f32 v[0:1], v[0:1], v[44:45] op_sel_hi:[1,0]
	s_nop 0
	v_pk_fma_f32 v[0:1], v[10:11], v[10:11], v[0:1]
	s_nop 0
	v_pk_add_f32 v[0:1], v[0:1], v[46:47] op_sel_hi:[1,0]
	s_nop 0
	v_pk_fma_f32 v[0:1], v[34:35], v[34:35], v[0:1]
	s_nop 0
	v_pk_add_f32 v[0:1], v[0:1], v[48:49] op_sel_hi:[1,0]
	s_nop 0
	v_pk_fma_f32 v[0:1], v[32:33], v[32:33], v[0:1]
	s_nop 0
	v_pk_add_f32 v[0:1], v[0:1], v[50:51] op_sel_hi:[1,0]
	s_nop 0
	v_pk_fma_f32 v[0:1], v[16:17], v[16:17], v[0:1]
	s_nop 0
	v_pk_add_f32 v[0:1], v[0:1], v[52:53] op_sel_hi:[1,0]
	s_nop 0
	v_pk_fma_f32 v[0:1], v[18:19], v[18:19], v[0:1]
	s_nop 0
	v_pk_add_f32 v[0:1], v[0:1], v[54:55] op_sel_hi:[1,0]
	s_nop 0
	v_pk_fma_f32 v[0:1], v[12:13], v[12:13], v[0:1]
	s_nop 0
	v_pk_add_f32 v[0:1], v[0:1], v[56:57] op_sel_hi:[1,0]
	s_nop 0
	v_pk_fma_f32 v[0:1], v[14:15], v[14:15], v[0:1]
	s_nop 0
	v_pk_add_f32 v[0:1], v[0:1], v[58:59] op_sel_hi:[1,0]
	s_nop 0
	v_pk_fma_f32 v[0:1], v[4:5], v[4:5], v[0:1]
	s_nop 0
	v_pk_add_f32 v[0:1], v[0:1], v[60:61] op_sel_hi:[1,0]
	s_nop 0
	v_pk_fma_f32 v[0:1], v[6:7], v[6:7], v[0:1]
	s_nop 0
	v_pk_add_f32 v[0:1], v[0:1], v[62:63] op_sel_hi:[1,0]
	s_nop 0
	v_pk_fma_f32 v[0:1], v[20:21], v[20:21], v[0:1]
	s_nop 0
	v_pk_add_f32 v[0:1], v[0:1], v[64:65] op_sel_hi:[1,0]
	s_nop 0
	v_pk_fma_f32 v[0:1], v[22:23], v[22:23], v[0:1]
	s_nop 0
	v_pk_add_f32 v[0:1], v[0:1], v[66:67] op_sel_hi:[1,0]
	s_nop 0
	v_mov_b32_e32 v1, v0
	s_nop 1
	v_permlane16_swap_b32_e32 v0, v1
	v_add_f32_e32 v0, v0, v1
	v_mov_b32_e32 v1, v0
	s_nop 1
	v_permlane32_swap_b32_e32 v0, v1
	v_add_f32_e32 v0, v0, v1
	v_fmamk_f32 v0, v0, 0x3c000000, v182
	v_mul_f32_e32 v1, 0x4b800000, v0
	v_cmp_gt_f32_e32 vcc, s40, v0
	s_nop 1
	v_cndmask_b32_e32 v0, v0, v1, vcc
	v_rsq_f32_e32 v2, v0
	v_lshl_add_u64 v[0:1], s[16:17], 0, v[78:79]
	v_lshl_add_u64 v[0:1], v[0:1], 0, s[46:47]
	v_lshl_add_u64 v[40:41], v[0:1], 0, v[124:125]
	v_mul_f32_e32 v0, 0x45800000, v2
	v_cndmask_b32_e32 v0, v2, v0, vcc
	v_mul_f32_e32 v42, 0x3f24fd5c, v0
	v_pk_mul_f32 v[0:1], v[36:37], v[42:43] op_sel_hi:[1,0]
	v_pk_mul_f32 v[2:3], v[38:39], v[42:43] op_sel_hi:[1,0]
	v_pk_mul_f32 v[0:1], v[24:25], v[0:1]
	v_pk_mul_f32 v[2:3], v[26:27], v[2:3]
	v_cvt_pk_bf16_f32 v0, v0, v1
	v_cvt_pk_bf16_f32 v1, v2, v3
	global_store_dwordx2 v[40:41], v[0:1], off offset:1024
	v_mov_b64_e32 v[0:1], v[218:219]
	v_mov_b64_e32 v[2:3], v[220:221]
	v_pk_mul_f32 v[24:25], v[28:29], v[42:43] op_sel_hi:[1,0]
	v_pk_mul_f32 v[26:27], v[30:31], v[42:43] op_sel_hi:[1,0]
	v_pk_mul_f32 v[8:9], v[8:9], v[42:43] op_sel_hi:[1,0]
	v_pk_mul_f32 v[10:11], v[10:11], v[42:43] op_sel_hi:[1,0]
	v_pk_mul_f32 v[4:5], v[4:5], v[42:43] op_sel_hi:[1,0]
	v_pk_mul_f32 v[6:7], v[6:7], v[42:43] op_sel_hi:[1,0]
	v_pk_mul_f32 v[0:1], v[0:1], v[24:25]
	v_pk_mul_f32 v[2:3], v[2:3], v[26:27]
	v_cvt_pk_bf16_f32 v0, v0, v1
	v_cvt_pk_bf16_f32 v1, v2, v3
	global_store_dwordx2 v[40:41], v[0:1], off offset:1056
	v_mov_b64_e32 v[0:1], v[222:223]
	v_mov_b64_e32 v[2:3], v[224:225]
	v_pk_mul_f32 v[0:1], v[8:9], v[0:1]
	v_pk_mul_f32 v[2:3], v[10:11], v[2:3]
	v_cvt_pk_bf16_f32 v0, v0, v1
	v_cvt_pk_bf16_f32 v1, v2, v3
	global_store_dwordx2 v[40:41], v[0:1], off offset:1088
	v_mov_b64_e32 v[0:1], v[226:227]
	v_mov_b64_e32 v[2:3], v[228:229]
	v_pk_mul_f32 v[8:9], v[34:35], v[42:43] op_sel_hi:[1,0]
	v_pk_mul_f32 v[10:11], v[32:33], v[42:43] op_sel_hi:[1,0]
	v_pk_mul_f32 v[0:1], v[8:9], v[0:1]
	v_pk_mul_f32 v[2:3], v[10:11], v[2:3]
	v_cvt_pk_bf16_f32 v0, v0, v1
	v_cvt_pk_bf16_f32 v1, v2, v3
	global_store_dwordx2 v[40:41], v[0:1], off offset:1120
	v_mov_b64_e32 v[0:1], v[230:231]
	v_mov_b64_e32 v[2:3], v[232:233]
	v_pk_mul_f32 v[8:9], v[16:17], v[42:43] op_sel_hi:[1,0]
	v_pk_mul_f32 v[10:11], v[18:19], v[42:43] op_sel_hi:[1,0]
	v_pk_mul_f32 v[0:1], v[8:9], v[0:1]
	v_pk_mul_f32 v[2:3], v[10:11], v[2:3]
	v_cvt_pk_bf16_f32 v0, v0, v1
	v_cvt_pk_bf16_f32 v1, v2, v3
	global_store_dwordx2 v[40:41], v[0:1], off offset:1152
	v_mov_b64_e32 v[0:1], v[234:235]
	v_mov_b64_e32 v[2:3], v[236:237]
	v_pk_mul_f32 v[8:9], v[12:13], v[42:43] op_sel_hi:[1,0]
	v_pk_mul_f32 v[10:11], v[14:15], v[42:43] op_sel_hi:[1,0]
	v_pk_mul_f32 v[0:1], v[8:9], v[0:1]
	v_pk_mul_f32 v[2:3], v[10:11], v[2:3]
	v_cvt_pk_bf16_f32 v0, v0, v1
	v_cvt_pk_bf16_f32 v1, v2, v3
	global_store_dwordx2 v[40:41], v[0:1], off offset:1184
	v_mov_b64_e32 v[0:1], v[238:239]
	v_mov_b64_e32 v[2:3], v[240:241]
	v_pk_mul_f32 v[0:1], v[4:5], v[0:1]
	v_pk_mul_f32 v[2:3], v[6:7], v[2:3]
	v_cvt_pk_bf16_f32 v0, v0, v1
	v_cvt_pk_bf16_f32 v1, v2, v3
	global_store_dwordx2 v[40:41], v[0:1], off offset:1216
	v_mov_b64_e32 v[0:1], v[242:243]
	v_mov_b64_e32 v[2:3], v[244:245]
	v_pk_mul_f32 v[4:5], v[20:21], v[42:43] op_sel_hi:[1,0]
	v_pk_mul_f32 v[6:7], v[22:23], v[42:43] op_sel_hi:[1,0]
	v_pk_mul_f32 v[0:1], v[4:5], v[0:1]
	v_pk_mul_f32 v[2:3], v[6:7], v[2:3]
	v_cvt_pk_bf16_f32 v0, v0, v1
	v_cvt_pk_bf16_f32 v1, v2, v3
	global_store_dwordx2 v[40:41], v[0:1], off offset:1248

.LBB0_1714:
	s_or_b64 exec, exec, s[2:3]
	s_waitcnt lgkmcnt(0)
	s_barrier
	s_and_saveexec_b64 s[0:1], vcc
	s_cbranch_execz .LBB0_1691
	v_readlane_b32 s76, v254, 50
	ds_read2st64_b32 v[72:73], v65 offset1:2
	ds_read2st64_b32 v[68:69], v65 offset0:4 offset1:6
	ds_read2st64_b32 v[74:75], v65 offset0:16 offset1:18
	ds_read2st64_b32 v[76:77], v65 offset0:20 offset1:22
	ds_read2st64_b32 v[78:79], v65 offset0:32 offset1:34
	ds_read2st64_b32 v[80:81], v65 offset0:36 offset1:38
	ds_read2st64_b32 v[82:83], v65 offset0:48 offset1:50
	ds_read2st64_b32 v[84:85], v65 offset0:52 offset1:54
	ds_read2st64_b32 v[86:87], v65 offset0:64 offset1:66
	ds_read2st64_b32 v[88:89], v65 offset0:68 offset1:70
	ds_read2st64_b32 v[90:91], v65 offset0:80 offset1:82
	ds_read2st64_b32 v[92:93], v65 offset0:84 offset1:86
	ds_read2st64_b32 v[94:95], v65 offset0:96 offset1:98
	ds_read2st64_b32 v[96:97], v65 offset0:100 offset1:102
	ds_read2st64_b32 v[98:99], v65 offset0:112 offset1:114
	ds_read2st64_b32 v[100:101], v65 offset0:116 offset1:118
	v_lshlrev_b32_e32 v67, 4, v131
	v_readlane_b32 s80, v254, 54
	v_readlane_b32 s81, v254, 55
	s_waitcnt lgkmcnt(14)
	v_pk_fma_f32 v[62:63], v[62:63], v[66:67], v[68:69] op_sel_hi:[1,0,1] neg_lo:[0,0,1] neg_hi:[0,0,1]
	v_pk_fma_f32 v[60:61], v[60:61], v[66:67], v[72:73] op_sel_hi:[1,0,1] neg_lo:[0,0,1] neg_hi:[0,0,1]
	v_mul_f32_e32 v104, v63, v63
	v_mul_f32_e32 v72, v61, v61
	v_pk_fma_f32 v[72:73], v[60:61], v[60:61], v[72:73] op_sel_hi:[1,1,0]
	global_load_dwordx4 v[68:71], v67, s[80:81]
	global_load_dwordx4 v[218:221], v67, s[80:81] offset:64
	global_load_dwordx4 v[222:225], v67, s[80:81] offset:128
	global_load_dwordx4 v[226:229], v67, s[80:81] offset:192
	global_load_dwordx4 v[230:233], v67, s[80:81] offset:256
	global_load_dwordx4 v[234:237], v67, s[80:81] offset:320
	global_load_dwordx4 v[238:241], v67, s[80:81] offset:384
	global_load_dwordx4 v[242:245], v67, s[80:81] offset:448
	global_load_dwordx4 v[246:249], v67, s[80:81]
	v_pk_fma_f32 v[72:73], v[62:63], v[62:63], v[72:73]
	s_waitcnt lgkmcnt(13)
	v_pk_fma_f32 v[48:49], v[48:49], v[66:67], v[74:75] op_sel_hi:[1,0,1] neg_lo:[0,0,1] neg_hi:[0,0,1]
	v_pk_add_f32 v[72:73], v[72:73], v[104:105] op_sel_hi:[1,0]
	v_mul_f32_e32 v74, v49, v49
	v_pk_fma_f32 v[72:73], v[48:49], v[48:49], v[72:73]
	s_waitcnt lgkmcnt(12)
	v_pk_fma_f32 v[50:51], v[50:51], v[66:67], v[76:77] op_sel_hi:[1,0,1] neg_lo:[0,0,1] neg_hi:[0,0,1]
	v_pk_add_f32 v[72:73], v[72:73], v[74:75] op_sel_hi:[1,0]
	v_mul_f32_e32 v74, v51, v51
	v_pk_fma_f32 v[72:73], v[50:51], v[50:51], v[72:73]
	s_waitcnt lgkmcnt(11)
	v_pk_fma_f32 v[40:41], v[40:41], v[66:67], v[78:79] op_sel_hi:[1,0,1] neg_lo:[0,0,1] neg_hi:[0,0,1]
	v_pk_add_f32 v[72:73], v[72:73], v[74:75] op_sel_hi:[1,0]
	v_mul_f32_e32 v74, v41, v41
	v_pk_fma_f32 v[72:73], v[40:41], v[40:41], v[72:73]
	s_waitcnt lgkmcnt(10)
	v_pk_fma_f32 v[42:43], v[42:43], v[66:67], v[80:81] op_sel_hi:[1,0,1] neg_lo:[0,0,1] neg_hi:[0,0,1]
	v_pk_add_f32 v[72:73], v[72:73], v[74:75] op_sel_hi:[1,0]
	v_mul_f32_e32 v74, v43, v43
	v_pk_fma_f32 v[72:73], v[42:43], v[42:43], v[72:73]
	s_waitcnt lgkmcnt(9)
	v_pk_fma_f32 v[76:77], v[32:33], v[66:67], v[82:83] op_sel_hi:[1,0,1] neg_lo:[0,0,1] neg_hi:[0,0,1]
	v_pk_add_f32 v[72:73], v[72:73], v[74:75] op_sel_hi:[1,0]
	s_waitcnt lgkmcnt(8)
	v_pk_fma_f32 v[74:75], v[34:35], v[66:67], v[84:85] op_sel_hi:[1,0,1] neg_lo:[0,0,1] neg_hi:[0,0,1]
	v_pk_fma_f32 v[32:33], v[76:77], v[76:77], v[72:73]
	v_mul_f32_e32 v34, v77, v77
	v_pk_add_f32 v[32:33], v[32:33], v[34:35] op_sel_hi:[1,0]
	v_mul_f32_e32 v34, v75, v75
	v_pk_fma_f32 v[32:33], v[74:75], v[74:75], v[32:33]
	s_waitcnt lgkmcnt(7)
	v_pk_fma_f32 v[52:53], v[52:53], v[66:67], v[86:87] op_sel_hi:[1,0,1] neg_lo:[0,0,1] neg_hi:[0,0,1]
	v_pk_add_f32 v[32:33], v[32:33], v[34:35] op_sel_hi:[1,0]
	v_mul_f32_e32 v34, v53, v53
	v_pk_fma_f32 v[32:33], v[52:53], v[52:53], v[32:33]
	s_waitcnt lgkmcnt(6)
	v_pk_fma_f32 v[54:55], v[54:55], v[66:67], v[88:89] op_sel_hi:[1,0,1] neg_lo:[0,0,1] neg_hi:[0,0,1]
	v_pk_add_f32 v[32:33], v[32:33], v[34:35] op_sel_hi:[1,0]
	v_mul_f32_e32 v34, v55, v55
	v_pk_fma_f32 v[32:33], v[54:55], v[54:55], v[32:33]
	s_waitcnt lgkmcnt(5)
	v_pk_fma_f32 v[44:45], v[44:45], v[66:67], v[90:91] op_sel_hi:[1,0,1] neg_lo:[0,0,1] neg_hi:[0,0,1]
	v_pk_add_f32 v[32:33], v[32:33], v[34:35] op_sel_hi:[1,0]
	v_mul_f32_e32 v34, v45, v45
	v_pk_fma_f32 v[32:33], v[44:45], v[44:45], v[32:33]
	s_waitcnt lgkmcnt(4)
	v_pk_fma_f32 v[46:47], v[46:47], v[66:67], v[92:93] op_sel_hi:[1,0,1] neg_lo:[0,0,1] neg_hi:[0,0,1]
	v_pk_add_f32 v[32:33], v[32:33], v[34:35] op_sel_hi:[1,0]
	v_mul_f32_e32 v34, v47, v47
	v_pk_fma_f32 v[32:33], v[46:47], v[46:47], v[32:33]
	s_waitcnt lgkmcnt(3)
	v_pk_fma_f32 v[36:37], v[36:37], v[66:67], v[94:95] op_sel_hi:[1,0,1] neg_lo:[0,0,1] neg_hi:[0,0,1]
	v_pk_add_f32 v[32:33], v[32:33], v[34:35] op_sel_hi:[1,0]
	v_mul_f32_e32 v34, v37, v37
	v_pk_fma_f32 v[32:33], v[36:37], v[36:37], v[32:33]
	s_waitcnt lgkmcnt(2)
	v_pk_fma_f32 v[38:39], v[38:39], v[66:67], v[96:97] op_sel_hi:[1,0,1] neg_lo:[0,0,1] neg_hi:[0,0,1]
	v_pk_add_f32 v[32:33], v[32:33], v[34:35] op_sel_hi:[1,0]
	v_mul_f32_e32 v34, v39, v39
	v_pk_fma_f32 v[32:33], v[38:39], v[38:39], v[32:33]
	s_waitcnt lgkmcnt(1)
	v_pk_fma_f32 v[56:57], v[56:57], v[66:67], v[98:99] op_sel_hi:[1,0,1] neg_lo:[0,0,1] neg_hi:[0,0,1]
	v_pk_add_f32 v[32:33], v[32:33], v[34:35] op_sel_hi:[1,0]
	v_mul_f32_e32 v34, v57, v57
	v_pk_fma_f32 v[32:33], v[56:57], v[56:57], v[32:33]
	s_waitcnt lgkmcnt(0)
	v_pk_fma_f32 v[58:59], v[58:59], v[66:67], v[100:101] op_sel_hi:[1,0,1] neg_lo:[0,0,1] neg_hi:[0,0,1]
	v_pk_add_f32 v[32:33], v[32:33], v[34:35] op_sel_hi:[1,0]
	v_mul_f32_e32 v34, v59, v59
	v_pk_fma_f32 v[32:33], v[58:59], v[58:59], v[32:33]
	v_readlane_b32 s4, v253, 50
	v_pk_add_f32 v[32:33], v[32:33], v[34:35] op_sel_hi:[1,0]
	v_lshlrev_b64 v[102:103], 11, v[134:135]
	v_mov_b32_e32 v33, v32
	s_nop 1
	v_permlane16_swap_b32_e32 v32, v33
	v_add_f32_e32 v32, v32, v33
	v_mov_b32_e32 v33, v32
	s_nop 1
	v_permlane32_swap_b32_e32 v32, v33
	v_add_f32_e32 v32, v32, v33
	v_fmamk_f32 v32, v32, 0x3c000000, v182
	v_mul_f32_e32 v33, 0x4b800000, v32
	v_cmp_gt_f32_e32 vcc, s40, v32
	v_readlane_b32 s16, v253, 62
	v_readlane_b32 s17, v253, 63
	v_cndmask_b32_e32 v32, v32, v33, vcc
	v_rsq_f32_e32 v34, v32
	v_lshl_add_u64 v[102:103], s[16:17], 0, v[102:103]
	s_lshl_b32 s46, s48, 1
	v_lshl_add_u64 v[32:33], v[102:103], 0, s[46:47]
	v_mov_b32_e32 v131, v129
	v_lshl_add_u64 v[72:73], v[32:33], 0, v[130:131]
	v_mul_f32_e32 v32, 0x45800000, v34
	v_cndmask_b32_e32 v32, v34, v32, vcc
	v_mul_f32_e32 v66, 0x3f24fd5c, v32
	v_pk_mul_f32 v[32:33], v[60:61], v[66:67] op_sel_hi:[1,0]
	v_pk_mul_f32 v[34:35], v[62:63], v[66:67] op_sel_hi:[1,0]
	s_waitcnt vmcnt(0)
	v_pk_mul_f32 v[32:33], v[68:69], v[32:33]
	v_pk_mul_f32 v[34:35], v[70:71], v[34:35]
	v_cvt_pk_bf16_f32 v32, v32, v33
	v_cvt_pk_bf16_f32 v33, v34, v35
	global_store_dwordx2 v[72:73], v[32:33], off offset:1024
	v_mov_b64_e32 v[32:33], v[218:219]
	v_mov_b64_e32 v[34:35], v[220:221]
	v_pk_mul_f32 v[48:49], v[48:49], v[66:67] op_sel_hi:[1,0]
	v_pk_mul_f32 v[50:51], v[50:51], v[66:67] op_sel_hi:[1,0]
	v_pk_mul_f32 v[40:41], v[40:41], v[66:67] op_sel_hi:[1,0]
	v_pk_mul_f32 v[42:43], v[42:43], v[66:67] op_sel_hi:[1,0]
	v_pk_mul_f32 v[36:37], v[36:37], v[66:67] op_sel_hi:[1,0]
	v_pk_mul_f32 v[38:39], v[38:39], v[66:67] op_sel_hi:[1,0]
	v_lshlrev_b64 v[78:79], 11, v[132:133]
	v_readlane_b32 s77, v254, 51
	v_readlane_b32 s78, v254, 52
	v_readlane_b32 s79, v254, 53
	v_readlane_b32 s82, v254, 56
	v_readlane_b32 s83, v254, 57
	v_readlane_b32 s84, v254, 58
	v_readlane_b32 s85, v254, 59
	v_readlane_b32 s86, v254, 60
	v_readlane_b32 s87, v254, 61
	v_readlane_b32 s88, v254, 62
	v_readlane_b32 s89, v254, 63
	v_readlane_b32 s90, v253, 0
	v_readlane_b32 s91, v253, 1
	v_readlane_b32 s5, v253, 51
	v_readlane_b32 s6, v253, 52
	v_readlane_b32 s7, v253, 53
	v_readlane_b32 s8, v253, 54
	v_readlane_b32 s9, v253, 55
	v_readlane_b32 s10, v253, 56
	v_readlane_b32 s11, v253, 57
	v_readlane_b32 s12, v253, 58
	v_readlane_b32 s13, v253, 59
	v_readlane_b32 s14, v253, 60
	v_readlane_b32 s15, v253, 61
	v_readlane_b32 s18, v255, 0
	v_readlane_b32 s19, v255, 1
	v_pk_mul_f32 v[32:33], v[32:33], v[48:49]
	v_pk_mul_f32 v[34:35], v[34:35], v[50:51]
	v_cvt_pk_bf16_f32 v32, v32, v33
	v_cvt_pk_bf16_f32 v33, v34, v35
	global_store_dwordx2 v[72:73], v[32:33], off offset:1056
	v_mov_b64_e32 v[32:33], v[222:223]
	v_mov_b64_e32 v[34:35], v[224:225]
	v_pk_mul_f32 v[32:33], v[40:41], v[32:33]
	v_pk_mul_f32 v[34:35], v[42:43], v[34:35]
	v_cvt_pk_bf16_f32 v32, v32, v33
	v_cvt_pk_bf16_f32 v33, v34, v35
	global_store_dwordx2 v[72:73], v[32:33], off offset:1088
	v_mov_b64_e32 v[32:33], v[226:227]
	v_mov_b64_e32 v[34:35], v[228:229]
	v_pk_mul_f32 v[40:41], v[76:77], v[66:67] op_sel_hi:[1,0]
	v_pk_mul_f32 v[42:43], v[74:75], v[66:67] op_sel_hi:[1,0]
	v_pk_mul_f32 v[32:33], v[40:41], v[32:33]
	v_pk_mul_f32 v[34:35], v[42:43], v[34:35]
	v_cvt_pk_bf16_f32 v32, v32, v33
	v_cvt_pk_bf16_f32 v33, v34, v35
	global_store_dwordx2 v[72:73], v[32:33], off offset:1120
	v_mov_b64_e32 v[32:33], v[230:231]
	v_mov_b64_e32 v[34:35], v[232:233]
	v_pk_mul_f32 v[40:41], v[52:53], v[66:67] op_sel_hi:[1,0]
	v_pk_mul_f32 v[42:43], v[54:55], v[66:67] op_sel_hi:[1,0]
	v_pk_mul_f32 v[32:33], v[40:41], v[32:33]
	v_pk_mul_f32 v[34:35], v[42:43], v[34:35]
	v_cvt_pk_bf16_f32 v32, v32, v33
	v_cvt_pk_bf16_f32 v33, v34, v35
	global_store_dwordx2 v[72:73], v[32:33], off offset:1152
	v_mov_b64_e32 v[32:33], v[234:235]
	v_mov_b64_e32 v[34:35], v[236:237]
	v_pk_mul_f32 v[40:41], v[44:45], v[66:67] op_sel_hi:[1,0]
	v_pk_mul_f32 v[42:43], v[46:47], v[66:67] op_sel_hi:[1,0]
	v_pk_mul_f32 v[32:33], v[40:41], v[32:33]
	v_pk_mul_f32 v[34:35], v[42:43], v[34:35]
	v_cvt_pk_bf16_f32 v32, v32, v33
	v_cvt_pk_bf16_f32 v33, v34, v35
	global_store_dwordx2 v[72:73], v[32:33], off offset:1184
	v_mov_b64_e32 v[32:33], v[238:239]
	v_mov_b64_e32 v[34:35], v[240:241]
	v_pk_mul_f32 v[32:33], v[36:37], v[32:33]
	v_pk_mul_f32 v[34:35], v[38:39], v[34:35]
	v_cvt_pk_bf16_f32 v32, v32, v33
	v_cvt_pk_bf16_f32 v33, v34, v35
	global_store_dwordx2 v[72:73], v[32:33], off offset:1216
	v_mov_b64_e32 v[32:33], v[242:243]
	v_mov_b64_e32 v[34:35], v[244:245]
	ds_read2st64_b32 v[36:37], v65 offset0:8 offset1:10
	ds_read2st64_b32 v[38:39], v65 offset0:12 offset1:14
	ds_read2st64_b32 v[40:41], v65 offset0:24 offset1:26
	ds_read2st64_b32 v[42:43], v65 offset0:28 offset1:30
	ds_read2st64_b32 v[44:45], v65 offset0:40 offset1:42
	ds_read2st64_b32 v[46:47], v65 offset0:44 offset1:46
	ds_read2st64_b32 v[48:49], v65 offset0:56 offset1:58
	ds_read2st64_b32 v[50:51], v65 offset0:60 offset1:62
	ds_read2st64_b32 v[52:53], v65 offset0:72 offset1:74
	ds_read2st64_b32 v[54:55], v65 offset0:76 offset1:78
	ds_read2st64_b32 v[60:61], v65 offset0:88 offset1:90
	ds_read2st64_b32 v[62:63], v65 offset0:92 offset1:94
	ds_read2st64_b32 v[68:69], v65 offset0:104 offset1:106
	ds_read2st64_b32 v[70:71], v65 offset0:108 offset1:110
	ds_read2st64_b32 v[74:75], v65 offset0:120 offset1:122
	ds_read2st64_b32 v[76:77], v65 offset0:124 offset1:126
	s_waitcnt lgkmcnt(14)
	v_pk_fma_f32 v[38:39], v[26:27], v[64:65], v[38:39] op_sel_hi:[1,0,1] neg_lo:[0,0,1] neg_hi:[0,0,1]
	v_pk_fma_f32 v[36:37], v[24:25], v[64:65], v[36:37] op_sel_hi:[1,0,1] neg_lo:[0,0,1] neg_hi:[0,0,1]
	v_pk_mul_f32 v[24:25], v[56:57], v[66:67] op_sel_hi:[1,0]
	v_pk_mul_f32 v[26:27], v[58:59], v[66:67] op_sel_hi:[1,0]
	s_waitcnt lgkmcnt(13)
	v_pk_fma_f32 v[28:29], v[28:29], v[64:65], v[40:41] op_sel_hi:[1,0,1] neg_lo:[0,0,1] neg_hi:[0,0,1]
	s_waitcnt lgkmcnt(12)
	v_pk_fma_f32 v[30:31], v[30:31], v[64:65], v[42:43] op_sel_hi:[1,0,1] neg_lo:[0,0,1] neg_hi:[0,0,1]
	v_mul_f32_e32 v40, v29, v29
	v_mul_f32_e32 v42, v31, v31
	s_waitcnt lgkmcnt(11)
	v_pk_fma_f32 v[8:9], v[8:9], v[64:65], v[44:45] op_sel_hi:[1,0,1] neg_lo:[0,0,1] neg_hi:[0,0,1]
	s_waitcnt lgkmcnt(10)
	v_pk_fma_f32 v[10:11], v[10:11], v[64:65], v[46:47] op_sel_hi:[1,0,1] neg_lo:[0,0,1] neg_hi:[0,0,1]
	v_mul_f32_e32 v44, v9, v9
	v_mul_f32_e32 v46, v11, v11
	s_waitcnt lgkmcnt(7)
	v_pk_fma_f32 v[16:17], v[16:17], v[64:65], v[52:53] op_sel_hi:[1,0,1] neg_lo:[0,0,1] neg_hi:[0,0,1]
	s_waitcnt lgkmcnt(6)
	v_pk_fma_f32 v[18:19], v[18:19], v[64:65], v[54:55] op_sel_hi:[1,0,1] neg_lo:[0,0,1] neg_hi:[0,0,1]
	v_mul_f32_e32 v52, v17, v17
	v_mul_f32_e32 v54, v19, v19
	s_waitcnt lgkmcnt(5)
	v_pk_fma_f32 v[12:13], v[12:13], v[64:65], v[60:61] op_sel_hi:[1,0,1] neg_lo:[0,0,1] neg_hi:[0,0,1]
	s_waitcnt lgkmcnt(4)
	v_pk_fma_f32 v[14:15], v[14:15], v[64:65], v[62:63] op_sel_hi:[1,0,1] neg_lo:[0,0,1] neg_hi:[0,0,1]
	v_mul_f32_e32 v56, v13, v13
	v_mul_f32_e32 v58, v15, v15
	s_waitcnt lgkmcnt(3)
	v_pk_fma_f32 v[4:5], v[4:5], v[64:65], v[68:69] op_sel_hi:[1,0,1] neg_lo:[0,0,1] neg_hi:[0,0,1]
	s_waitcnt lgkmcnt(2)
	v_pk_fma_f32 v[6:7], v[6:7], v[64:65], v[70:71] op_sel_hi:[1,0,1] neg_lo:[0,0,1] neg_hi:[0,0,1]
	v_mul_f32_e32 v60, v5, v5
	v_mul_f32_e32 v62, v7, v7
	s_waitcnt lgkmcnt(1)
	v_pk_fma_f32 v[20:21], v[20:21], v[64:65], v[74:75] op_sel_hi:[1,0,1] neg_lo:[0,0,1] neg_hi:[0,0,1]
	s_waitcnt lgkmcnt(0)
	v_pk_fma_f32 v[22:23], v[22:23], v[64:65], v[76:77] op_sel_hi:[1,0,1] neg_lo:[0,0,1] neg_hi:[0,0,1]
	v_pk_mul_f32 v[24:25], v[24:25], v[32:33]
	v_pk_mul_f32 v[26:27], v[26:27], v[34:35]
	v_cvt_pk_bf16_f32 v24, v24, v25
	v_cvt_pk_bf16_f32 v25, v26, v27
	global_store_dwordx2 v[72:73], v[24:25], off offset:1248
	v_mov_b64_e32 v[24:25], v[246:247]
	v_mov_b64_e32 v[26:27], v[248:249]
	v_pk_fma_f32 v[34:35], v[0:1], v[64:65], v[48:49] op_sel_hi:[1,0,1] neg_lo:[0,0,1] neg_hi:[0,0,1]
	v_mul_f32_e32 v0, v37, v37
	v_pk_fma_f32 v[0:1], v[36:37], v[36:37], v[0:1] op_sel_hi:[1,1,0]
	v_pk_fma_f32 v[32:33], v[2:3], v[64:65], v[50:51] op_sel_hi:[1,0,1] neg_lo:[0,0,1] neg_hi:[0,0,1]
	v_mul_f32_e32 v2, v39, v39
	v_pk_fma_f32 v[0:1], v[38:39], v[38:39], v[0:1]
	v_mul_f32_e32 v48, v35, v35
	v_pk_add_f32 v[0:1], v[0:1], v[2:3] op_sel_hi:[1,0]
	v_mul_f32_e32 v50, v33, v33
	v_pk_fma_f32 v[0:1], v[28:29], v[28:29], v[0:1]
	v_mul_f32_e32 v64, v21, v21
	v_pk_add_f32 v[0:1], v[0:1], v[40:41] op_sel_hi:[1,0]
	v_mul_f32_e32 v66, v23, v23
	v_pk_fma_f32 v[0:1], v[30:31], v[30:31], v[0:1]
	s_nop 0
	v_pk_add_f32 v[0:1], v[0:1], v[42:43] op_sel_hi:[1,0]
	s_nop 0
	v_pk_fma_f32 v[0:1], v[8:9], v[8:9], v[0:1]
	s_nop 0
	v_pk_add_f32 v[0:1], v[0:1], v[44:45] op_sel_hi:[1,0]
	s_nop 0
	v_pk_fma_f32 v[0:1], v[10:11], v[10:11], v[0:1]
	s_nop 0
	v_pk_add_f32 v[0:1], v[0:1], v[46:47] op_sel_hi:[1,0]
	s_nop 0
	v_pk_fma_f32 v[0:1], v[34:35], v[34:35], v[0:1]
	s_nop 0
	v_pk_add_f32 v[0:1], v[0:1], v[48:49] op_sel_hi:[1,0]
	s_nop 0
	v_pk_fma_f32 v[0:1], v[32:33], v[32:33], v[0:1]
	s_nop 0
	v_pk_add_f32 v[0:1], v[0:1], v[50:51] op_sel_hi:[1,0]
	s_nop 0
	v_pk_fma_f32 v[0:1], v[16:17], v[16:17], v[0:1]
	s_nop 0
	v_pk_add_f32 v[0:1], v[0:1], v[52:53] op_sel_hi:[1,0]
	s_nop 0
	v_pk_fma_f32 v[0:1], v[18:19], v[18:19], v[0:1]
	s_nop 0
	v_pk_add_f32 v[0:1], v[0:1], v[54:55] op_sel_hi:[1,0]
	s_nop 0
	v_pk_fma_f32 v[0:1], v[12:13], v[12:13], v[0:1]
	s_nop 0
	v_pk_add_f32 v[0:1], v[0:1], v[56:57] op_sel_hi:[1,0]
	s_nop 0
	v_pk_fma_f32 v[0:1], v[14:15], v[14:15], v[0:1]
	s_nop 0
	v_pk_add_f32 v[0:1], v[0:1], v[58:59] op_sel_hi:[1,0]
	s_nop 0
	v_pk_fma_f32 v[0:1], v[4:5], v[4:5], v[0:1]
	s_nop 0
	v_pk_add_f32 v[0:1], v[0:1], v[60:61] op_sel_hi:[1,0]
	s_nop 0
	v_pk_fma_f32 v[0:1], v[6:7], v[6:7], v[0:1]
	s_nop 0
	v_pk_add_f32 v[0:1], v[0:1], v[62:63] op_sel_hi:[1,0]
	s_nop 0
	v_pk_fma_f32 v[0:1], v[20:21], v[20:21], v[0:1]
	s_nop 0
	v_pk_add_f32 v[0:1], v[0:1], v[64:65] op_sel_hi:[1,0]
	s_nop 0
	v_pk_fma_f32 v[0:1], v[22:23], v[22:23], v[0:1]
	s_nop 0
	v_pk_add_f32 v[0:1], v[0:1], v[66:67] op_sel_hi:[1,0]
	s_nop 0
	v_mov_b32_e32 v1, v0
	s_nop 1
	v_permlane16_swap_b32_e32 v0, v1
	v_add_f32_e32 v0, v0, v1
	v_mov_b32_e32 v1, v0
	s_nop 1
	v_permlane32_swap_b32_e32 v0, v1
	v_add_f32_e32 v0, v0, v1
	v_fmamk_f32 v0, v0, 0x3c000000, v182
	v_mul_f32_e32 v1, 0x4b800000, v0
	v_cmp_gt_f32_e32 vcc, s40, v0
	s_nop 1
	v_cndmask_b32_e32 v0, v0, v1, vcc
	v_rsq_f32_e32 v2, v0
	v_lshl_add_u64 v[0:1], s[16:17], 0, v[78:79]
	v_lshl_add_u64 v[0:1], v[0:1], 0, s[46:47]
	v_lshl_add_u64 v[40:41], v[0:1], 0, v[130:131]
	v_mul_f32_e32 v0, 0x45800000, v2
	v_cndmask_b32_e32 v0, v2, v0, vcc
	v_mul_f32_e32 v42, 0x3f24fd5c, v0
	v_pk_mul_f32 v[0:1], v[36:37], v[42:43] op_sel_hi:[1,0]
	v_pk_mul_f32 v[2:3], v[38:39], v[42:43] op_sel_hi:[1,0]
	v_pk_mul_f32 v[0:1], v[24:25], v[0:1]
	v_pk_mul_f32 v[2:3], v[26:27], v[2:3]
	v_cvt_pk_bf16_f32 v0, v0, v1
	v_cvt_pk_bf16_f32 v1, v2, v3
	global_store_dwordx2 v[40:41], v[0:1], off offset:1024
	v_mov_b64_e32 v[0:1], v[218:219]
	v_mov_b64_e32 v[2:3], v[220:221]
	v_pk_mul_f32 v[24:25], v[28:29], v[42:43] op_sel_hi:[1,0]
	v_pk_mul_f32 v[26:27], v[30:31], v[42:43] op_sel_hi:[1,0]
	v_pk_mul_f32 v[8:9], v[8:9], v[42:43] op_sel_hi:[1,0]
	v_pk_mul_f32 v[10:11], v[10:11], v[42:43] op_sel_hi:[1,0]
	v_pk_mul_f32 v[4:5], v[4:5], v[42:43] op_sel_hi:[1,0]
	v_pk_mul_f32 v[6:7], v[6:7], v[42:43] op_sel_hi:[1,0]
	v_pk_mul_f32 v[0:1], v[0:1], v[24:25]
	v_pk_mul_f32 v[2:3], v[2:3], v[26:27]
	v_cvt_pk_bf16_f32 v0, v0, v1
	v_cvt_pk_bf16_f32 v1, v2, v3
	global_store_dwordx2 v[40:41], v[0:1], off offset:1056
	v_mov_b64_e32 v[0:1], v[222:223]
	v_mov_b64_e32 v[2:3], v[224:225]
	v_pk_mul_f32 v[0:1], v[8:9], v[0:1]
	v_pk_mul_f32 v[2:3], v[10:11], v[2:3]
	v_cvt_pk_bf16_f32 v0, v0, v1
	v_cvt_pk_bf16_f32 v1, v2, v3
	global_store_dwordx2 v[40:41], v[0:1], off offset:1088
	v_mov_b64_e32 v[0:1], v[226:227]
	v_mov_b64_e32 v[2:3], v[228:229]
	v_pk_mul_f32 v[8:9], v[34:35], v[42:43] op_sel_hi:[1,0]
	v_pk_mul_f32 v[10:11], v[32:33], v[42:43] op_sel_hi:[1,0]
	v_pk_mul_f32 v[0:1], v[8:9], v[0:1]
	v_pk_mul_f32 v[2:3], v[10:11], v[2:3]
	v_cvt_pk_bf16_f32 v0, v0, v1
	v_cvt_pk_bf16_f32 v1, v2, v3
	global_store_dwordx2 v[40:41], v[0:1], off offset:1120
	v_mov_b64_e32 v[0:1], v[230:231]
	v_mov_b64_e32 v[2:3], v[232:233]
	v_pk_mul_f32 v[8:9], v[16:17], v[42:43] op_sel_hi:[1,0]
	v_pk_mul_f32 v[10:11], v[18:19], v[42:43] op_sel_hi:[1,0]
	v_pk_mul_f32 v[0:1], v[8:9], v[0:1]
	v_pk_mul_f32 v[2:3], v[10:11], v[2:3]
	v_cvt_pk_bf16_f32 v0, v0, v1
	v_cvt_pk_bf16_f32 v1, v2, v3
	global_store_dwordx2 v[40:41], v[0:1], off offset:1152
	v_mov_b64_e32 v[0:1], v[234:235]
	v_mov_b64_e32 v[2:3], v[236:237]
	v_pk_mul_f32 v[8:9], v[12:13], v[42:43] op_sel_hi:[1,0]
	v_pk_mul_f32 v[10:11], v[14:15], v[42:43] op_sel_hi:[1,0]
	v_pk_mul_f32 v[0:1], v[8:9], v[0:1]
	v_pk_mul_f32 v[2:3], v[10:11], v[2:3]
	v_cvt_pk_bf16_f32 v0, v0, v1
	v_cvt_pk_bf16_f32 v1, v2, v3
	global_store_dwordx2 v[40:41], v[0:1], off offset:1184
	v_mov_b64_e32 v[0:1], v[238:239]
	v_mov_b64_e32 v[2:3], v[240:241]
	v_pk_mul_f32 v[0:1], v[4:5], v[0:1]
	v_pk_mul_f32 v[2:3], v[6:7], v[2:3]
	v_cvt_pk_bf16_f32 v0, v0, v1
	v_cvt_pk_bf16_f32 v1, v2, v3
	global_store_dwordx2 v[40:41], v[0:1], off offset:1216
	v_mov_b64_e32 v[0:1], v[242:243]
	v_mov_b64_e32 v[2:3], v[244:245]
	v_pk_mul_f32 v[4:5], v[20:21], v[42:43] op_sel_hi:[1,0]
	v_pk_mul_f32 v[6:7], v[22:23], v[42:43] op_sel_hi:[1,0]
	v_pk_mul_f32 v[0:1], v[4:5], v[0:1]
	v_pk_mul_f32 v[2:3], v[6:7], v[2:3]
	v_cvt_pk_bf16_f32 v0, v0, v1
	v_cvt_pk_bf16_f32 v1, v2, v3
	global_store_dwordx2 v[40:41], v[0:1], off offset:1248
	s_branch .LBB0_1691
